# P1 main K-loop head aligned to 64 B (.p2align 6), otherwise the saddr-epilogue version
# baseline (speedup 1.0000x reference)
.Lp1pk_w2_done:
	s_waitcnt lgkmcnt(0)
	s_barrier
	s_setprio 1
	s_waitcnt lgkmcnt(0)
	v_mfma_f32_16x16x32_bf16 v[30:33], v[146:149], v[194:197], 0
	v_mfma_f32_16x16x32_bf16 v[26:29], v[160:163], v[194:197], 0
	v_mfma_f32_16x16x32_bf16 v[22:25], v[146:149], v[202:205], 0
	v_mfma_f32_16x16x32_bf16 v[18:21], v[160:163], v[202:205], 0
	v_mfma_f32_16x16x32_bf16 v[14:17], v[146:149], v[218:221], 0
	v_mfma_f32_16x16x32_bf16 v[10:13], v[160:163], v[218:221], 0
	v_mfma_f32_16x16x32_bf16 v[6:9], v[146:149], v[226:229], 0
	v_mfma_f32_16x16x32_bf16 v[2:5], v[160:163], v[226:229], 0
	v_mfma_f32_16x16x32_bf16 v[30:33], v[156:159], v[198:201], v[30:33]
	v_mfma_f32_16x16x32_bf16 v[26:29], v[174:177], v[198:201], v[26:29]
	v_mfma_f32_16x16x32_bf16 v[22:25], v[156:159], v[206:209], v[22:25]
	v_mfma_f32_16x16x32_bf16 v[18:21], v[174:177], v[206:209], v[18:21]
	v_mfma_f32_16x16x32_bf16 v[14:17], v[156:159], v[222:225], v[14:17]
	v_mfma_f32_16x16x32_bf16 v[10:13], v[174:177], v[222:225], v[10:13]
	v_mfma_f32_16x16x32_bf16 v[6:9], v[156:159], v[230:233], v[6:9]
	v_mfma_f32_16x16x32_bf16 v[2:5], v[174:177], v[230:233], v[2:5]
	s_setprio 0
	s_setprio 1
	v_mfma_f32_16x16x32_bf16 v[94:97], v[178:181], v[194:197], 0
	v_mfma_f32_16x16x32_bf16 v[90:93], v[186:189], v[194:197], 0
	v_mfma_f32_16x16x32_bf16 v[86:89], v[178:181], v[202:205], 0
	v_mfma_f32_16x16x32_bf16 v[82:85], v[186:189], v[202:205], 0
	v_mfma_f32_16x16x32_bf16 v[78:81], v[178:181], v[218:221], 0
	v_mfma_f32_16x16x32_bf16 v[74:77], v[186:189], v[218:221], 0
	v_mfma_f32_16x16x32_bf16 v[54:57], v[178:181], v[226:229], 0
	v_mfma_f32_16x16x32_bf16 v[34:37], v[186:189], v[226:229], 0
	v_mfma_f32_16x16x32_bf16 v[94:97], v[182:185], v[198:201], v[94:97]
	v_mfma_f32_16x16x32_bf16 v[90:93], v[190:193], v[198:201], v[90:93]
	v_mfma_f32_16x16x32_bf16 v[86:89], v[182:185], v[206:209], v[86:89]
	v_mfma_f32_16x16x32_bf16 v[82:85], v[190:193], v[206:209], v[82:85]
	v_mfma_f32_16x16x32_bf16 v[78:81], v[182:185], v[222:225], v[78:81]
	v_mfma_f32_16x16x32_bf16 v[74:77], v[190:193], v[222:225], v[74:77]
	v_mfma_f32_16x16x32_bf16 v[54:57], v[182:185], v[230:233], v[54:57]
	v_mfma_f32_16x16x32_bf16 v[34:37], v[190:193], v[230:233], v[34:37]
	s_setprio 0
	s_barrier
	s_add_i32 s63, 0, 0x18000
	v_add_u32_e32 v172, s63, v153
	s_add_i32 s64, 0, 0x1c000
	ds_read_b128 v[146:149], v172
	ds_read_b128 v[156:159], v172 offset:1024
	ds_read_b128 v[160:163], v172 offset:2048
	ds_read_b128 v[174:177], v172 offset:3072
	v_add_u32_e32 v172, s64, v153
	ds_read_b128 v[178:181], v172
	ds_read_b128 v[182:185], v172 offset:1024
	ds_read_b128 v[186:189], v172 offset:2048
	ds_read_b128 v[190:193], v172 offset:3072
	s_add_u32 s30, s50, 0x80000
	s_addc_u32 s31, s51, 0
	s_mov_b32 m0, s29
	ds_read_b128 v[194:197], v155 offset:32768
	ds_read_b128 v[198:201], v155 offset:33792
	ds_read_b128 v[202:205], v155 offset:34816
	ds_read_b128 v[206:209], v155 offset:35840
	ds_read_b128 v[218:221], v155 offset:36864
	ds_read_b128 v[222:225], v155 offset:37888
	ds_read_b128 v[226:229], v155 offset:38912
	ds_read_b128 v[230:233], v155 offset:39936
	global_load_lds_dwordx4 v136, s[30:31]
	v_lshl_add_u64 v[172:173], s[30:31], 0, v[132:133]
	s_mov_b32 m0, s35
	s_nop 0
	global_load_lds_dwordx4 v132, s[30:31]
	s_waitcnt vmcnt(8)
	s_waitcnt lgkmcnt(0)
	s_barrier
	s_setprio 1
	s_waitcnt lgkmcnt(0)
	v_mfma_f32_16x16x32_bf16 v[70:73], v[146:149], v[194:197], v[70:73]
	v_mfma_f32_16x16x32_bf16 v[66:69], v[160:163], v[194:197], v[66:69]
	v_mfma_f32_16x16x32_bf16 v[62:65], v[146:149], v[202:205], v[62:65]
	v_mfma_f32_16x16x32_bf16 v[58:61], v[160:163], v[202:205], v[58:61]
	v_mfma_f32_16x16x32_bf16 v[50:53], v[146:149], v[218:221], v[50:53]
	v_mfma_f32_16x16x32_bf16 v[46:49], v[160:163], v[218:221], v[46:49]
	v_mfma_f32_16x16x32_bf16 v[42:45], v[146:149], v[226:229], v[42:45]
	v_mfma_f32_16x16x32_bf16 v[38:41], v[160:163], v[226:229], v[38:41]
	v_mfma_f32_16x16x32_bf16 v[70:73], v[156:159], v[198:201], v[70:73]
	v_mfma_f32_16x16x32_bf16 v[66:69], v[174:177], v[198:201], v[66:69]
	v_mfma_f32_16x16x32_bf16 v[62:65], v[156:159], v[206:209], v[62:65]
	v_mfma_f32_16x16x32_bf16 v[58:61], v[174:177], v[206:209], v[58:61]
	v_mfma_f32_16x16x32_bf16 v[50:53], v[156:159], v[222:225], v[50:53]
	v_mfma_f32_16x16x32_bf16 v[46:49], v[174:177], v[222:225], v[46:49]
	v_mfma_f32_16x16x32_bf16 v[42:45], v[156:159], v[230:233], v[42:45]
	v_mfma_f32_16x16x32_bf16 v[38:41], v[174:177], v[230:233], v[38:41]
	s_setprio 0
	s_setprio 1
	v_mfma_f32_16x16x32_bf16 v[126:129], v[178:181], v[194:197], v[126:129]
	v_mfma_f32_16x16x32_bf16 v[122:125], v[186:189], v[194:197], v[122:125]
	v_mfma_f32_16x16x32_bf16 v[118:121], v[178:181], v[202:205], v[118:121]
	v_mfma_f32_16x16x32_bf16 v[114:117], v[186:189], v[202:205], v[114:117]
	v_mfma_f32_16x16x32_bf16 v[110:113], v[178:181], v[218:221], v[110:113]
	v_mfma_f32_16x16x32_bf16 v[106:109], v[186:189], v[218:221], v[106:109]
	v_mfma_f32_16x16x32_bf16 v[102:105], v[178:181], v[226:229], v[102:105]
	v_mfma_f32_16x16x32_bf16 v[98:101], v[186:189], v[226:229], v[98:101]
	v_mfma_f32_16x16x32_bf16 v[126:129], v[182:185], v[198:201], v[126:129]
	v_mfma_f32_16x16x32_bf16 v[122:125], v[190:193], v[198:201], v[122:125]
	v_mfma_f32_16x16x32_bf16 v[118:121], v[182:185], v[206:209], v[118:121]
	v_mfma_f32_16x16x32_bf16 v[114:117], v[190:193], v[206:209], v[114:117]
	v_mfma_f32_16x16x32_bf16 v[110:113], v[182:185], v[222:225], v[110:113]
	v_mfma_f32_16x16x32_bf16 v[106:109], v[190:193], v[222:225], v[106:109]
	v_mfma_f32_16x16x32_bf16 v[102:105], v[182:185], v[230:233], v[102:105]
	v_mfma_f32_16x16x32_bf16 v[98:101], v[190:193], v[230:233], v[98:101]
	s_setprio 0
	s_barrier
	s_add_i32 s30, s63, s8
	s_add_i32 m0, s30, 0xffffff80
	ds_read_b128 v[194:197], v155 offset:49152
	ds_read_b128 v[198:201], v155 offset:50176
	ds_read_b128 v[202:205], v155 offset:51200
	ds_read_b128 v[206:209], v155 offset:52224
	ds_read_b128 v[218:221], v155 offset:53248
	ds_read_b128 v[222:225], v155 offset:54272
	ds_read_b128 v[226:229], v155 offset:55296
	ds_read_b128 v[230:233], v155 offset:56320
	global_load_lds_dwordx4 v134, s[48:49] offset:128
	s_add_i32 m0, s30, 0x1f80
	s_add_u32 s30, s48, 0x80080
	s_addc_u32 s31, s49, 0
	s_add_i32 s48, s64, s8
	global_load_lds_dwordx4 v130, s[80:81] offset:128
	s_mov_b32 m0, s48
	s_nop 0
	global_load_lds_dwordx4 v134, s[30:31]
	s_add_i32 m0, s48, 0x2000
	s_nop 0
	global_load_lds_dwordx4 v130, s[30:31]
	s_add_i32 m0, s52, 0xffffff80
	s_nop 0
	global_load_lds_dwordx4 v136, s[50:51] offset:128
	v_lshl_add_u64 v[150:151], v[170:171], 0, s[24:25]
	s_add_i32 m0, s53, 0xffffff80
	s_nop 0
	global_load_lds_dwordx4 v132, s[50:51] offset:128
	s_waitcnt vmcnt(8)
	s_waitcnt lgkmcnt(0)
	s_barrier
	s_setprio 1
	s_waitcnt lgkmcnt(0)
	v_mfma_f32_16x16x32_bf16 v[30:33], v[146:149], v[194:197], v[30:33]
	v_mfma_f32_16x16x32_bf16 v[26:29], v[160:163], v[194:197], v[26:29]
	v_mfma_f32_16x16x32_bf16 v[22:25], v[146:149], v[202:205], v[22:25]
	v_mfma_f32_16x16x32_bf16 v[18:21], v[160:163], v[202:205], v[18:21]
	v_mfma_f32_16x16x32_bf16 v[14:17], v[146:149], v[218:221], v[14:17]
	v_mfma_f32_16x16x32_bf16 v[10:13], v[160:163], v[218:221], v[10:13]
	v_mfma_f32_16x16x32_bf16 v[6:9], v[146:149], v[226:229], v[6:9]
	v_mfma_f32_16x16x32_bf16 v[2:5], v[160:163], v[226:229], v[2:5]
	v_mfma_f32_16x16x32_bf16 v[30:33], v[156:159], v[198:201], v[30:33]
	v_mfma_f32_16x16x32_bf16 v[26:29], v[174:177], v[198:201], v[26:29]
	v_mfma_f32_16x16x32_bf16 v[22:25], v[156:159], v[206:209], v[22:25]
	v_mfma_f32_16x16x32_bf16 v[18:21], v[174:177], v[206:209], v[18:21]
	v_mfma_f32_16x16x32_bf16 v[14:17], v[156:159], v[222:225], v[14:17]
	v_mfma_f32_16x16x32_bf16 v[10:13], v[174:177], v[222:225], v[10:13]
	v_mfma_f32_16x16x32_bf16 v[6:9], v[156:159], v[230:233], v[6:9]
	v_mfma_f32_16x16x32_bf16 v[2:5], v[174:177], v[230:233], v[2:5]
	s_setprio 0
	s_setprio 1
	v_mfma_f32_16x16x32_bf16 v[94:97], v[178:181], v[194:197], v[94:97]
	v_mfma_f32_16x16x32_bf16 v[90:93], v[186:189], v[194:197], v[90:93]
	v_mfma_f32_16x16x32_bf16 v[86:89], v[178:181], v[202:205], v[86:89]
	v_mfma_f32_16x16x32_bf16 v[82:85], v[186:189], v[202:205], v[82:85]
	v_mfma_f32_16x16x32_bf16 v[78:81], v[178:181], v[218:221], v[78:81]
	v_mfma_f32_16x16x32_bf16 v[74:77], v[186:189], v[218:221], v[74:77]
	v_mfma_f32_16x16x32_bf16 v[54:57], v[178:181], v[226:229], v[54:57]
	v_mfma_f32_16x16x32_bf16 v[34:37], v[186:189], v[226:229], v[34:37]
	v_mfma_f32_16x16x32_bf16 v[94:97], v[182:185], v[198:201], v[94:97]
	v_mfma_f32_16x16x32_bf16 v[90:93], v[190:193], v[198:201], v[90:93]
	v_mfma_f32_16x16x32_bf16 v[86:89], v[182:185], v[206:209], v[86:89]
	v_mfma_f32_16x16x32_bf16 v[82:85], v[190:193], v[206:209], v[82:85]
	v_mfma_f32_16x16x32_bf16 v[78:81], v[182:185], v[222:225], v[78:81]
	v_mfma_f32_16x16x32_bf16 v[74:77], v[190:193], v[222:225], v[74:77]
	v_mfma_f32_16x16x32_bf16 v[54:57], v[182:185], v[230:233], v[54:57]
	v_mfma_f32_16x16x32_bf16 v[34:37], v[190:193], v[230:233], v[34:37]
	s_setprio 0
	s_barrier
	s_add_i32 s62, s62, 2
	s_add_u32 s60, s60, 0x100
	s_addc_u32 s61, s61, 0
	s_add_u32 s0, s0, 0x100
	s_addc_u32 s1, s1, 0
	s_cmp_gt_u32 s62, 29
	.p2align	6
